# v85 + P0 tail: w_sp load issued before the x-loop, small-parameter conversion moved to the last 7 workgroups
# speedup vs baseline: 1.0062x; 1.0062x over previous
; __device__ __forceinline__ unsigned f2bf(float f) { unsigned u = __builtin_bit_cast(unsigned, f); return (u + 0x7fffu + ((u >> 16) & 1u)) >> 16; }
; __device__ __forceinline__ unsigned pk2(float lo, float hi) { return pg8::cvt_pk_bf16(lo, hi); }
; __global__ void __launch_bounds__(NT, 2) fwd_mega(Args A) {
;     ...
;         for (int m = gw; m < T; m += NGW) {
;             const float* xrow = (m < 8192) ? A.xp + (size_t)m * D : A.xs + (size_t)(m - 8192) * D;
;             const f32x4* xr = (const f32x4*)xrow + lane; f32x4 v[8]; float s = 0.f;
; #pragma unroll
;             for (int j = 0; j < 8; ++j) { v[j] = __builtin_nontemporal_load(xr + 64 * j); s += (v[j][0] * v[j][0] + v[j][1] * v[j][1]) + (v[j][2] * v[j][2] + v[j][3] * v[j][3]); }
;             s = wave_sum(s);
;             if (lane == 0) r1[m] = 1.0f / sqrtf(s * (1.0f / D) + pg8::EPSN);
;             v2u* o8 = (v2u*)(XB + (size_t)m * D) + lane;
; #pragma unroll
;             for (int j = 0; j < 8; ++j) { v2u w; w.x = pk2(v[j][0], v[j][1]); w.y = pk2(v[j][2], v[j][3]); o8[64 * j] = w; }
;         }
;         const int gt = vcu * NT + tid, NGT = G * NT;
;         for (int i = gt; i < 8 * 128 * 128; i += NGT) ((bf16*)(ws + WS_WSP))[i] = (bf16)f2bf(A.w_sp[i]);
.Lcva_fin:
.Lcva_end:
.LBB0_59:
	v_lshl_add_u32 v240, s3, 9, v160
	v_ashrrev_i32_e32 v241, 31, v240
	v_lshl_add_u64 v[242:243], v[240:241], 2, s[10:11]
	global_load_dword v244, v[242:243], off
	v_cmp_eq_u32_e64 s[86:87], 0, v160
	v_mov_b32_e32 v245, 0
	v_mov_b32_e32 v247, 0x10000
	s_and_saveexec_b64 s[84:85], s[86:87]
	global_load_dword v245, v247, s[34:35] sc1
	s_or_b64 exec, exec, s[84:85]
	s_cmpk_gt_i32 s58, 0x3fff
	v_mbcnt_lo_u32_b32 v161, -1, 0
	s_cbranch_scc1 .LBB0_64
	v_mbcnt_hi_u32_b32 v0, -1, v161
	v_and_b32_e32 v1, 64, v0
	v_add_u32_e32 v1, 64, v1
	v_xor_b32_e32 v2, 1, v0
	v_cmp_lt_i32_e32 vcc, v2, v1
	s_ashr_i32 s59, s58, 31
	s_lshl_b64 s[0:1], s[58:59], 12
	v_cndmask_b32_e32 v2, v0, v2, vcc
	v_lshlrev_b32_e32 v36, 2, v2
	v_xor_b32_e32 v2, 2, v0
	v_cmp_lt_i32_e32 vcc, v2, v1
	s_ashr_i32 s53, s52, 31
	v_lshl_or_b32 v34, v152, 3, s0
	v_cndmask_b32_e32 v2, v0, v2, vcc
	v_lshlrev_b32_e32 v37, 2, v2
	v_xor_b32_e32 v2, 4, v0
	v_cmp_lt_i32_e32 vcc, v2, v1
	v_mov_b32_e32 v35, s1
	s_lshl_b64 s[40:41], s[52:53], 12
	v_cndmask_b32_e32 v2, v0, v2, vcc
	v_lshlrev_b32_e32 v38, 2, v2
	v_xor_b32_e32 v2, 8, v0
	v_cmp_lt_i32_e32 vcc, v2, v1
	s_lshl_b64 s[0:1], s[58:59], 2
	s_add_u32 s0, s0, 0x30000
	v_cndmask_b32_e32 v2, v0, v2, vcc
	v_lshlrev_b32_e32 v39, 2, v2
	v_xor_b32_e32 v2, 16, v0
	v_cmp_lt_i32_e32 vcc, v2, v1
	v_mov_b32_e32 v33, 0
	v_cmp_eq_u32_e64 s[4:5], 0, v152
	v_cndmask_b32_e32 v2, v0, v2, vcc
	v_lshlrev_b32_e32 v40, 2, v2
	v_xor_b32_e32 v2, 32, v0
	v_cmp_lt_i32_e32 vcc, v2, v1
	s_addc_u32 s1, s1, 0
	s_lshl_b64 s[42:43], s[52:53], 2
	v_cndmask_b32_e32 v0, v0, v2, vcc
	v_lshlrev_b32_e32 v41, 2, v0
	v_lshlrev_b32_e32 v32, 4, v152
	s_movk_i32 s62, 0x1000
	v_mov_b32_e32 v42, 0x358637bd
	s_mov_b32 s63, 0xf800000
	v_mov_b32_e32 v43, 0x260
	s_branch .LBB0_62
